# conv_item LDS fill: the six serialized row-chunk loads issued together (counted wait, same data)
# speedup vs baseline: 1.0026x; 1.0026x over previous
.LBB0_293:
	s_mov_b32 s10, 0x3727c5ac
	v_mov_b32_e32 v0, v169
	s_lshl_b32 s69, s68, 6
	s_and_saveexec_b64 s[2:3], s[38:39]
	s_cbranch_execz .LBB0_292
	s_and_b32 s40, s69, 0xfc0
	s_and_b32 s34, s69, 0xfffff000
	s_add_i32 s40, s40, -15
	s_add_u32 s4, s50, 0x6a00600
	s_addc_u32 s5, s51, 0
	v_ashrrev_i32_e32 v176, 5, v170
	v_add_u32_e32 v177, s40, v176
	v_lshl_add_u32 v178, v176, 9, v152
	v_mov_b32_e32 v179, v177
	v_cmp_gt_u32_e32 vcc, s18, v179
	v_mov_b32_e32 v208, 0
	v_mov_b32_e32 v209, 0
	v_mov_b32_e32 v210, 0
	v_mov_b32_e32 v211, 0
	v_or_b32_e32 v180, s34, v179
	v_mul_u32_u24_e32 v180, 0x1800, v180
	v_add_u32_e32 v180, v180, v168
	s_and_saveexec_b64 s[6:7], vcc
	s_cbranch_execz .Lcf_skip0
	global_load_dwordx4 v[208:211], v180, s[4:5]
.Lcf_skip0:
	s_or_b64 exec, exec, s[6:7]
	v_add_u32_e32 v179, 16, v177
	v_cmp_gt_u32_e32 vcc, s18, v179
	v_mov_b32_e32 v212, 0
	v_mov_b32_e32 v213, 0
	v_mov_b32_e32 v214, 0
	v_mov_b32_e32 v215, 0
	v_or_b32_e32 v180, s34, v179
	v_mul_u32_u24_e32 v180, 0x1800, v180
	v_add_u32_e32 v180, v180, v168
	s_and_saveexec_b64 s[6:7], vcc
	s_cbranch_execz .Lcf_skip1
	global_load_dwordx4 v[212:215], v180, s[4:5]
.Lcf_skip1:
	s_or_b64 exec, exec, s[6:7]
	v_add_u32_e32 v179, 32, v177
	v_cmp_gt_u32_e32 vcc, s18, v179
	v_mov_b32_e32 v216, 0
	v_mov_b32_e32 v217, 0
	v_mov_b32_e32 v218, 0
	v_mov_b32_e32 v219, 0
	v_or_b32_e32 v180, s34, v179
	v_mul_u32_u24_e32 v180, 0x1800, v180
	v_add_u32_e32 v180, v180, v168
	s_and_saveexec_b64 s[6:7], vcc
	s_cbranch_execz .Lcf_skip2
	global_load_dwordx4 v[216:219], v180, s[4:5]
.Lcf_skip2:
	s_or_b64 exec, exec, s[6:7]
	v_add_u32_e32 v179, 48, v177
	v_cmp_gt_u32_e32 vcc, s18, v179
	v_mov_b32_e32 v220, 0
	v_mov_b32_e32 v221, 0
	v_mov_b32_e32 v222, 0
	v_mov_b32_e32 v223, 0
	v_or_b32_e32 v180, s34, v179
	v_mul_u32_u24_e32 v180, 0x1800, v180
	v_add_u32_e32 v180, v180, v168
	s_and_saveexec_b64 s[6:7], vcc
	s_cbranch_execz .Lcf_skip3
	global_load_dwordx4 v[220:223], v180, s[4:5]
.Lcf_skip3:
	s_or_b64 exec, exec, s[6:7]
	v_add_u32_e32 v179, 64, v177
	v_cmp_gt_u32_e32 vcc, s18, v179
	v_mov_b32_e32 v224, 0
	v_mov_b32_e32 v225, 0
	v_mov_b32_e32 v226, 0
	v_mov_b32_e32 v227, 0
	v_or_b32_e32 v180, s34, v179
	v_mul_u32_u24_e32 v180, 0x1800, v180
	v_add_u32_e32 v180, v180, v168
	s_and_saveexec_b64 s[6:7], vcc
	s_cbranch_execz .Lcf_skip4
	global_load_dwordx4 v[224:227], v180, s[4:5]
.Lcf_skip4:
	s_or_b64 exec, exec, s[6:7]
	v_add_u32_e32 v179, 80, v177
	v_cmp_gt_u32_e32 vcc, s18, v179
	s_mov_b64 s[6:7], vcc
	v_cmp_gt_u32_e32 vcc, 0x1c0, v170
	s_and_b64 vcc, vcc, s[6:7]
	v_mov_b32_e32 v228, 0
	v_mov_b32_e32 v229, 0
	v_mov_b32_e32 v230, 0
	v_mov_b32_e32 v231, 0
	v_or_b32_e32 v180, s34, v179
	v_mul_u32_u24_e32 v180, 0x1800, v180
	v_add_u32_e32 v180, v180, v168
	s_and_saveexec_b64 s[6:7], vcc
	s_cbranch_execz .Lcf_skip5
	global_load_dwordx4 v[228:231], v180, s[4:5]
.Lcf_skip5:
	s_or_b64 exec, exec, s[6:7]
	s_waitcnt vmcnt(0)
	ds_write_b128 v178, v[208:211]
	ds_write_b128 v178, v[212:215] offset:8192
	ds_write_b128 v178, v[216:219] offset:16384
	ds_write_b128 v178, v[220:223] offset:24576
	ds_write_b128 v178, v[224:227] offset:32768
	v_cmp_gt_u32_e32 vcc, 0x1c0, v170
	s_and_saveexec_b64 s[6:7], vcc
	ds_write_b128 v178, v[228:231] offset:40960
	s_or_b64 exec, exec, s[6:7]
	s_branch .LBB0_292
